# priority raise also around the three LDS-DMA GEMM k-loops of the merge phase (not their epilogues)
# speedup vs baseline: 1.0030x; 1.0030x over previous
; __device__ __forceinline__ float sigmoidf_(float x) { return 1.0f / (1.0f + __expf(-x)); }
; __device__ __forceinline__ void phase_g2(const Params& p, int l, f16* smem) {
;     ...
;     for (int x = 0; x < 3; ++x) {
;       f16x4 sg[4][4];
;       {
;         f32x4 ag[4][4];
;         zero_acc<4>(ag);
;         gemm_tile_dma<4>(HP + (size_t)m0 * DM, DM, WG + (size_t)(x * DM + n0) * DM, DM, DM, ag, sA, TIDX(p));
; #pragma unroll
;         for (int i = 0; i < 4; ++i)
; #pragma unroll
;           for (int j = 0; j < 4; ++j)
; #pragma unroll
;             for (int r = 0; r < 4; ++r) sg[i][j][r] = (f16)sigmoidf_(ag[i][j][r]);
;       }
;       __builtin_amdgcn_sched_barrier(0);
;       const f16* wo = (const f16*)(p.ws + (x == 0 ? WT_RO_OFF : (x == 1 ? WT_PO_OFF : WT_NO_OFF)));
;       const int kx = x == 1 ? 256 : RD;
;       const int aoff = x == 0 ? 0 : (x == 1 ? RD : 640);
; #pragma unroll
;       for (int h = 0; h < 2; ++h) {
;         f32x4 ab[4][2];
;         zero_acc<2>(ab);
;         gemm_tile_dma<2, true>(BR + (size_t)m0 * DM + aoff, DM, wo + (size_t)(n0 + h * 32) * kx, kx, kx, ab, sA, TIDX(p));
; #pragma unroll
;         for (int i = 0; i < 4; ++i)
; #pragma unroll
;           for (int j = 0; j < 2; ++j)
; #pragma unroll
;             for (int r = 0; r < 4; ++r) am[i][h * 2 + j][r] = (f16)((float)am[i][h * 2 + j][r] + (float)sg[i][h * 2 + j][r] * ab[i][j][r]);
;       }
;     }
.LBB0_1114:
	s_setprio 0
	v_pk_add_f32 v[150:151], v[148:149], 1.0 op_sel_hi:[1,0]
	v_add_f32_e32 v215, 1.0, v215
	v_add_f32_e32 v214, 1.0, v214
	v_pk_add_f32 v[132:133], v[132:133], 1.0 op_sel_hi:[1,0]
	v_pk_add_f32 v[130:131], v[130:131], 1.0 op_sel_hi:[1,0]
	v_rcp_f32_e32 v149, v151
	s_nop 0
	v_mul_f32_e32 v148, 1.0, v149
	v_pk_add_f32 v[128:129], v[128:129], 1.0 op_sel_hi:[1,0]
	v_pk_add_f32 v[126:127], v[126:127], 1.0 op_sel_hi:[1,0]
	v_pk_add_f32 v[124:125], v[124:125], 1.0 op_sel_hi:[1,0]
	v_rcp_f32_e32 v151, v150
	s_nop 0
	v_mul_f32_e32 v149, 1.0, v151
	v_pk_add_f32 v[150:151], v[146:147], 1.0 op_sel_hi:[1,0]
	v_pk_add_f32 v[122:123], v[122:123], 1.0 op_sel_hi:[1,0]
	v_pk_add_f32 v[120:121], v[120:121], 1.0 op_sel_hi:[1,0]
	v_cvt_pk_f16_f32 v148, v149, v148
	v_pk_add_f32 v[118:119], v[118:119], 1.0 op_sel_hi:[1,0]
	v_rcp_f32_e32 v147, v151
	s_nop 0
	v_mul_f32_e32 v146, 1.0, v147
	s_add_i32 s9, s9, 1
	s_addk_i32 s14, 0x400
	s_cmp_eq_u32 s9, 3
	v_rcp_f32_e32 v151, v150
	s_nop 0
	v_mul_f32_e32 v147, 1.0, v151
	v_pk_add_f32 v[150:151], v[144:145], 1.0 op_sel_hi:[1,0]
	v_cvt_pk_f16_f32 v146, v147, v146
	s_nop 0
	v_rcp_f32_e32 v145, v151
	s_nop 0
	v_mul_f32_e32 v144, 1.0, v145
	s_nop 0
	v_rcp_f32_e32 v151, v150
	s_nop 0
	v_mul_f32_e32 v145, 1.0, v151
	v_pk_add_f32 v[150:151], v[142:143], 1.0 op_sel_hi:[1,0]
	v_cvt_pk_f16_f32 v144, v145, v144
	s_nop 0
	v_rcp_f32_e32 v143, v151
	s_nop 0
	v_mul_f32_e32 v142, 1.0, v143
	s_nop 0
	v_rcp_f32_e32 v151, v150
	s_nop 0
	v_mul_f32_e32 v143, 1.0, v151
	v_add_f32_e32 v150, 1.0, v221
	v_cvt_pk_f16_f32 v142, v143, v142
	v_rcp_f32_e32 v152, v150
	s_nop 0
	v_mul_f32_e32 v151, 1.0, v152
	v_mov_b32_e32 v150, v151
	v_add_f32_e32 v151, 1.0, v220
	s_nop 0
	v_rcp_f32_e32 v153, v151
	s_nop 0
	v_mul_f32_e32 v152, 1.0, v153
	v_mov_b32_e32 v151, v152
	v_add_f32_e32 v152, 1.0, v219
	s_nop 0
	v_rcp_f32_e32 v154, v152
	s_nop 0
	v_mul_f32_e32 v153, 1.0, v154
	v_mov_b32_e32 v152, v153
	v_add_f32_e32 v153, 1.0, v218
	s_nop 0
	v_rcp_f32_e32 v155, v153
	s_nop 0
	v_mul_f32_e32 v154, 1.0, v155
	v_mov_b32_e32 v153, v154
	v_pk_add_f32 v[154:155], v[140:141], 1.0 op_sel_hi:[1,0]
	s_nop 0
	s_nop 0
	v_rcp_f32_e32 v141, v155
	s_nop 0
	v_mul_f32_e32 v140, 1.0, v141
	s_nop 0
	v_rcp_f32_e32 v155, v154
	s_nop 0
	v_mul_f32_e32 v141, 1.0, v155
	v_pk_add_f32 v[154:155], v[138:139], 1.0 op_sel_hi:[1,0]
	v_cvt_pk_f16_f32 v140, v141, v140
	s_nop 0
	v_rcp_f32_e32 v139, v155
	s_nop 0
	v_mul_f32_e32 v138, 1.0, v139
	s_nop 0
	v_rcp_f32_e32 v155, v154
	s_nop 0
	v_mul_f32_e32 v139, 1.0, v155
	v_pk_add_f32 v[154:155], v[136:137], 1.0 op_sel_hi:[1,0]
	v_cvt_pk_f16_f32 v138, v139, v138
	s_nop 0
	v_rcp_f32_e32 v137, v155
	s_nop 0
	v_mul_f32_e32 v136, 1.0, v137
	s_nop 0
	v_rcp_f32_e32 v155, v154
	s_nop 0
	v_mul_f32_e32 v137, 1.0, v155
	v_pk_add_f32 v[154:155], v[134:135], 1.0 op_sel_hi:[1,0]
	v_cvt_pk_f16_f32 v139, v137, v136
	v_cvt_f32_f16_e32 v136, v148
	v_cvt_f32_f16_sdwa v137, v148 dst_sel:DWORD dst_unused:UNUSED_PAD src0_sel:WORD_1
	v_rcp_f32_e32 v135, v155
	s_nop 0
	v_mul_f32_e32 v134, 1.0, v135
	s_nop 0
	v_rcp_f32_e32 v155, v154
	s_nop 0
	v_mul_f32_e32 v135, 1.0, v155
	v_add_f32_e32 v154, 1.0, v217
	v_cvt_pk_f16_f32 v141, v135, v134
	v_cvt_f32_f16_sdwa v135, v112 dst_sel:DWORD dst_unused:UNUSED_PAD src0_sel:WORD_1
	v_cvt_f32_f16_e32 v134, v112
	v_rcp_f32_e32 v217, v154
	s_nop 0
	v_mul_f32_e32 v155, 1.0, v217
	v_mov_b32_e32 v154, v155
	v_add_f32_e32 v155, 1.0, v216
	v_pk_fma_f32 v[60:61], v[60:61], v[136:137], v[134:135]
	v_cvt_f32_f16_e32 v134, v146
	v_cvt_pk_f16_f32 v112, v60, v61
	v_rcp_f32_e32 v217, v155
	s_nop 0
	v_mul_f32_e32 v216, 1.0, v217
	v_mov_b32_e32 v155, v216
	v_cvt_f32_f16_sdwa v61, v113 dst_sel:DWORD dst_unused:UNUSED_PAD src0_sel:WORD_1
	v_cvt_f32_f16_e32 v60, v113
	v_cvt_f32_f16_sdwa v135, v146 dst_sel:DWORD dst_unused:UNUSED_PAD src0_sel:WORD_1
	v_rcp_f32_e32 v217, v215
	s_nop 0
	v_mul_f32_e32 v216, 1.0, v217
	v_mov_b32_e32 v215, v216
	v_pk_fma_f32 v[60:61], v[62:63], v[134:135], v[60:61]
	v_cvt_f32_f16_e32 v62, v144
	v_cvt_pk_f16_f32 v113, v60, v61
	v_rcp_f32_e32 v217, v214
	s_nop 0
	v_mul_f32_e32 v216, 1.0, v217
	v_mov_b32_e32 v214, v216
	v_cvt_f32_f16_sdwa v61, v108 dst_sel:DWORD dst_unused:UNUSED_PAD src0_sel:WORD_1
	v_cvt_f32_f16_e32 v60, v108
	v_cvt_f32_f16_sdwa v63, v144 dst_sel:DWORD dst_unused:UNUSED_PAD src0_sel:WORD_1
	v_rcp_f32_e32 v217, v133
	s_nop 0
	v_mul_f32_e32 v216, 1.0, v217
	v_pk_fma_f32 v[56:57], v[56:57], v[62:63], v[60:61]
	v_cvt_f32_f16_e32 v60, v142
	v_cvt_pk_f16_f32 v108, v56, v57
	v_rcp_f32_e32 v217, v132
	s_nop 0
	v_mul_f32_e32 v133, 1.0, v217
	v_mov_b32_e32 v217, v133
	v_cvt_f32_f16_sdwa v57, v109 dst_sel:DWORD dst_unused:UNUSED_PAD src0_sel:WORD_1
	v_cvt_f32_f16_e32 v56, v109
	v_cvt_f32_f16_sdwa v61, v142 dst_sel:DWORD dst_unused:UNUSED_PAD src0_sel:WORD_1
	v_rcp_f32_e32 v133, v131
	s_nop 0
	v_mul_f32_e32 v132, 1.0, v133
	v_mov_b32_e32 v218, v132
	v_pk_fma_f32 v[56:57], v[58:59], v[60:61], v[56:57]
	v_cvt_f32_f16_e32 v58, v140
	v_cvt_pk_f16_f32 v109, v56, v57
	v_rcp_f32_e32 v132, v130
	s_nop 0
	v_mul_f32_e32 v131, 1.0, v132
	v_mov_b32_e32 v219, v131
	v_cvt_f32_f16_sdwa v57, v102 dst_sel:DWORD dst_unused:UNUSED_PAD src0_sel:WORD_1
	v_cvt_f32_f16_e32 v56, v102
	v_cvt_f32_f16_sdwa v59, v140 dst_sel:DWORD dst_unused:UNUSED_PAD src0_sel:WORD_1
	v_rcp_f32_e32 v131, v129
	s_nop 0
	v_mul_f32_e32 v130, 1.0, v131
	v_mov_b32_e32 v220, v130
	v_pk_fma_f32 v[52:53], v[52:53], v[58:59], v[56:57]
	v_cvt_f32_f16_e32 v56, v138
	v_cvt_pk_f16_f32 v102, v52, v53
	v_rcp_f32_e32 v130, v128
	s_nop 0
	v_mul_f32_e32 v129, 1.0, v130
	v_mov_b32_e32 v221, v129
	v_cvt_f32_f16_sdwa v53, v103 dst_sel:DWORD dst_unused:UNUSED_PAD src0_sel:WORD_1
; __device__ __forceinline__ float sigmoidf_(float x) { return 1.0f / (1.0f + __expf(-x)); }
; __device__ __forceinline__ void phase_g2(const Params& p, int l, f16* smem) {
;     ...
;     for (int x = 0; x < 3; ++x) {
;       f16x4 sg[4][4];
;       {
;         f32x4 ag[4][4];
;         zero_acc<4>(ag);
;         gemm_tile_dma<4>(HP + (size_t)m0 * DM, DM, WG + (size_t)(x * DM + n0) * DM, DM, DM, ag, sA, TIDX(p));
; #pragma unroll
;         for (int i = 0; i < 4; ++i)
; #pragma unroll
;           for (int j = 0; j < 4; ++j)
; #pragma unroll
;             for (int r = 0; r < 4; ++r) sg[i][j][r] = (f16)sigmoidf_(ag[i][j][r]);
;       }
;       __builtin_amdgcn_sched_barrier(0);
;       const f16* wo = (const f16*)(p.ws + (x == 0 ? WT_RO_OFF : (x == 1 ? WT_PO_OFF : WT_NO_OFF)));
;       const int kx = x == 1 ? 256 : RD;
;       const int aoff = x == 0 ? 0 : (x == 1 ? RD : 640);
; #pragma unroll
;       for (int h = 0; h < 2; ++h) {
;         f32x4 ab[4][2];
;         zero_acc<2>(ab);
;         gemm_tile_dma<2, true>(BR + (size_t)m0 * DM + aoff, DM, wo + (size_t)(n0 + h * 32) * kx, kx, kx, ab, sA, TIDX(p));
; #pragma unroll
;         for (int i = 0; i < 4; ++i)
; #pragma unroll
;           for (int j = 0; j < 2; ++j)
; #pragma unroll
;             for (int r = 0; r < 4; ++r) am[i][h * 2 + j][r] = (f16)((float)am[i][h * 2 + j][r] + (float)sg[i][h * 2 + j][r] * ab[i][j][r]);
;       }
;     }
	v_cvt_f32_f16_e32 v52, v103
	v_cvt_f32_f16_sdwa v57, v138 dst_sel:DWORD dst_unused:UNUSED_PAD src0_sel:WORD_1
	v_rcp_f32_e32 v129, v127
	s_nop 0
	v_mul_f32_e32 v128, 1.0, v129
	v_mov_b32_e32 v222, v128
	v_pk_fma_f32 v[52:53], v[54:55], v[56:57], v[52:53]
	v_cvt_f32_f16_e32 v54, v139
	v_cvt_pk_f16_f32 v103, v52, v53
	v_rcp_f32_e32 v128, v126
	s_nop 0
	v_mul_f32_e32 v127, 1.0, v128
	v_mov_b32_e32 v223, v127
	v_add_f32_e32 v126, 1.0, v213
	v_cvt_f32_f16_sdwa v53, v100 dst_sel:DWORD dst_unused:UNUSED_PAD src0_sel:WORD_1
	v_cvt_f32_f16_e32 v52, v100
	v_cvt_f32_f16_sdwa v55, v139 dst_sel:DWORD dst_unused:UNUSED_PAD src0_sel:WORD_1
	v_rcp_f32_e32 v128, v126
	s_nop 0
	v_mul_f32_e32 v127, 1.0, v128
	v_mov_b32_e32 v213, v127
	v_add_f32_e32 v126, 1.0, v212
	v_pk_fma_f32 v[48:49], v[48:49], v[54:55], v[52:53]
	v_cvt_f32_f16_e32 v52, v141
	v_cvt_pk_f16_f32 v100, v48, v49
	v_rcp_f32_e32 v128, v126
	s_nop 0
	v_mul_f32_e32 v127, 1.0, v128
	v_mov_b32_e32 v212, v127
	v_add_f32_e32 v126, 1.0, v211
	v_cvt_f32_f16_sdwa v49, v101 dst_sel:DWORD dst_unused:UNUSED_PAD src0_sel:WORD_1
	v_cvt_f32_f16_e32 v48, v101
	v_cvt_f32_f16_sdwa v53, v141 dst_sel:DWORD dst_unused:UNUSED_PAD src0_sel:WORD_1
	v_rcp_f32_e32 v128, v126
	s_nop 0
	v_mul_f32_e32 v127, 1.0, v128
	v_mov_b32_e32 v211, v127
	v_add_f32_e32 v126, 1.0, v210
	v_cvt_pk_f16_f32 v143, v217, v216
	v_pk_fma_f32 v[48:49], v[50:51], v[52:53], v[48:49]
	v_cvt_f32_f16_e32 v50, v143
	v_rcp_f32_e32 v128, v126
	s_nop 0
	v_mul_f32_e32 v127, 1.0, v128
	v_mov_b32_e32 v210, v127
	v_cvt_pk_f16_f32 v101, v48, v49
	v_cvt_f32_f16_sdwa v49, v94 dst_sel:DWORD dst_unused:UNUSED_PAD src0_sel:WORD_1
	v_cvt_f32_f16_e32 v48, v94
	v_rcp_f32_e32 v127, v125
	s_nop 0
	v_mul_f32_e32 v126, 1.0, v127
	v_mov_b32_e32 v224, v126
	v_cvt_f32_f16_sdwa v51, v143 dst_sel:DWORD dst_unused:UNUSED_PAD src0_sel:WORD_1
	v_cvt_pk_f16_f32 v145, v219, v218
	v_cvt_pk_f16_f32 v147, v221, v220
	v_rcp_f32_e32 v126, v124
	s_nop 0
	v_mul_f32_e32 v125, 1.0, v126
	v_mov_b32_e32 v225, v125
	v_pk_fma_f32 v[44:45], v[44:45], v[50:51], v[48:49]
	v_cvt_f32_f16_e32 v48, v145
	v_cvt_pk_f16_f32 v94, v44, v45
	v_rcp_f32_e32 v125, v123
	s_nop 0
	v_mul_f32_e32 v124, 1.0, v125
	v_mov_b32_e32 v226, v124
	v_cvt_f32_f16_sdwa v45, v95 dst_sel:DWORD dst_unused:UNUSED_PAD src0_sel:WORD_1
	v_cvt_f32_f16_e32 v44, v95
	v_cvt_f32_f16_sdwa v49, v145 dst_sel:DWORD dst_unused:UNUSED_PAD src0_sel:WORD_1
	v_rcp_f32_e32 v124, v122
	s_nop 0
	v_mul_f32_e32 v123, 1.0, v124
	v_mov_b32_e32 v227, v123
	v_pk_fma_f32 v[44:45], v[46:47], v[48:49], v[44:45]
	v_cvt_f32_f16_e32 v46, v147
	v_cvt_pk_f16_f32 v95, v44, v45
	v_rcp_f32_e32 v123, v121
	s_nop 0
	v_mul_f32_e32 v122, 1.0, v123
	v_mov_b32_e32 v121, v122
	v_cvt_f32_f16_sdwa v45, v92 dst_sel:DWORD dst_unused:UNUSED_PAD src0_sel:WORD_1
	v_cvt_f32_f16_e32 v44, v92
	v_cvt_f32_f16_sdwa v47, v147 dst_sel:DWORD dst_unused:UNUSED_PAD src0_sel:WORD_1
	v_rcp_f32_e32 v123, v120
	s_nop 0
	v_mul_f32_e32 v122, 1.0, v123
	v_mov_b32_e32 v120, v122
	v_cvt_pk_f16_f32 v149, v223, v222
	v_pk_fma_f32 v[40:41], v[40:41], v[46:47], v[44:45]
	v_cvt_f32_f16_e32 v44, v149
	v_rcp_f32_e32 v123, v119
	s_nop 0
	v_mul_f32_e32 v122, 1.0, v123
	v_mov_b32_e32 v119, v122
	v_cvt_pk_f16_f32 v92, v40, v41
	v_cvt_f32_f16_sdwa v41, v93 dst_sel:DWORD dst_unused:UNUSED_PAD src0_sel:WORD_1
	v_cvt_f32_f16_e32 v40, v93
	v_rcp_f32_e32 v123, v118
	s_nop 0
	v_mul_f32_e32 v122, 1.0, v123
	v_mov_b32_e32 v118, v122
	v_add_f32_e32 v122, 1.0, v209
	v_cvt_f32_f16_sdwa v45, v149 dst_sel:DWORD dst_unused:UNUSED_PAD src0_sel:WORD_1
	v_cvt_f16_f32_e32 v133, v150
	v_cvt_pk_f16_f32 v150, v225, v224
	v_rcp_f32_e32 v124, v122
	s_nop 0
	v_mul_f32_e32 v123, 1.0, v124
	v_mov_b32_e32 v209, v123
	v_add_f32_e32 v122, 1.0, v208
	v_pk_fma_f32 v[40:41], v[42:43], v[44:45], v[40:41]
	v_cvt_f32_f16_e32 v42, v150
	v_cvt_pk_f16_f32 v93, v40, v41
	v_rcp_f32_e32 v124, v122
	v_cvt_f32_f16_sdwa v41, v86 dst_sel:DWORD dst_unused:UNUSED_PAD src0_sel:WORD_1
	v_cvt_f32_f16_e32 v40, v86
	v_cvt_f32_f16_sdwa v43, v150 dst_sel:DWORD dst_unused:UNUSED_PAD src0_sel:WORD_1
	s_nop 0
	v_mul_f32_e32 v123, 1.0, v124
	v_mov_b32_e32 v208, v123
	v_add_f32_e32 v122, 1.0, v207
	v_cvt_f16_f32_e32 v132, v151
	v_cvt_pk_f16_f32 v151, v227, v226
	v_pk_fma_f32 v[36:37], v[36:37], v[42:43], v[40:41]
	v_cvt_f32_f16_e32 v40, v151
	v_cvt_pk_f16_f32 v86, v36, v37
	v_cvt_f32_f16_sdwa v37, v87 dst_sel:DWORD dst_unused:UNUSED_PAD src0_sel:WORD_1
	v_cvt_f32_f16_e32 v36, v87
	v_cvt_f32_f16_sdwa v41, v151 dst_sel:DWORD dst_unused:UNUSED_PAD src0_sel:WORD_1
	v_rcp_f32_e32 v124, v122
	v_cvt_f16_f32_e32 v131, v152
	v_cvt_pk_f16_f32 v152, v120, v121
	v_pk_fma_f32 v[36:37], v[38:39], v[40:41], v[36:37]
	v_cvt_pk_f16_f32 v87, v36, v37
	v_cvt_f32_f16_sdwa v37, v84 dst_sel:DWORD dst_unused:UNUSED_PAD src0_sel:WORD_1
	v_cvt_f32_f16_e32 v36, v84
	v_cvt_f32_f16_e32 v38, v152
	v_cvt_f32_f16_sdwa v39, v152 dst_sel:DWORD dst_unused:UNUSED_PAD src0_sel:WORD_1
	s_nop 0
	v_mul_f32_e32 v123, 1.0, v124
	v_cvt_f16_f32_e32 v130, v153
	v_cvt_pk_f16_f32 v153, v118, v119
	v_pk_fma_f32 v[32:33], v[32:33], v[38:39], v[36:37]
	v_mov_b32_e32 v207, v123
	v_add_f32_e32 v122, 1.0, v206
	v_cvt_pk_f16_f32 v84, v32, v33
	v_cvt_f32_f16_sdwa v33, v85 dst_sel:DWORD dst_unused:UNUSED_PAD src0_sel:WORD_1
	v_cvt_f32_f16_e32 v32, v85
	v_cvt_f32_f16_e32 v36, v153
	v_cvt_f32_f16_sdwa v37, v153 dst_sel:DWORD dst_unused:UNUSED_PAD src0_sel:WORD_1
	v_pk_fma_f32 v[32:33], v[34:35], v[36:37], v[32:33]
	v_cvt_f16_f32_e32 v129, v154
	v_cvt_pk_f16_f32 v85, v32, v33
	v_add_f32_e32 v32, 1.0, v205
	v_rcp_f32_e32 v124, v122
	s_nop 0
	v_mul_f32_e32 v123, 1.0, v124
	v_rcp_f32_e32 v34, v32
	s_nop 0
	v_mul_f32_e32 v33, 1.0, v34
; __device__ __forceinline__ float sigmoidf_(float x) { return 1.0f / (1.0f + __expf(-x)); }
; __device__ __forceinline__ void phase_g2(const Params& p, int l, f16* smem) {
;     ...
;     for (int x = 0; x < 3; ++x) {
;       f16x4 sg[4][4];
;       {
;         f32x4 ag[4][4];
;         zero_acc<4>(ag);
;         gemm_tile_dma<4>(HP + (size_t)m0 * DM, DM, WG + (size_t)(x * DM + n0) * DM, DM, DM, ag, sA, TIDX(p));
; #pragma unroll
;         for (int i = 0; i < 4; ++i)
; #pragma unroll
;           for (int j = 0; j < 4; ++j)
; #pragma unroll
;             for (int r = 0; r < 4; ++r) sg[i][j][r] = (f16)sigmoidf_(ag[i][j][r]);
;       }
;       __builtin_amdgcn_sched_barrier(0);
;       const f16* wo = (const f16*)(p.ws + (x == 0 ? WT_RO_OFF : (x == 1 ? WT_PO_OFF : WT_NO_OFF)));
;       const int kx = x == 1 ? 256 : RD;
;       const int aoff = x == 0 ? 0 : (x == 1 ? RD : 640);
; #pragma unroll
;       for (int h = 0; h < 2; ++h) {
;         f32x4 ab[4][2];
;         zero_acc<2>(ab);
;         gemm_tile_dma<2, true>(BR + (size_t)m0 * DM + aoff, DM, wo + (size_t)(n0 + h * 32) * kx, kx, kx, ab, sA, TIDX(p));
; #pragma unroll
;         for (int i = 0; i < 4; ++i)
; #pragma unroll
;           for (int j = 0; j < 2; ++j)
; #pragma unroll
;             for (int r = 0; r < 4; ++r) am[i][h * 2 + j][r] = (f16)((float)am[i][h * 2 + j][r] + (float)sg[i][h * 2 + j][r] * ab[i][j][r]);
;       }
;     }
	v_mov_b32_e32 v32, v33
	v_add_f32_e32 v33, 1.0, v204
	v_cvt_f16_f32_e32 v128, v155
	v_cvt_f16_f32_e32 v127, v215
	v_cvt_f16_f32_e32 v126, v214
	v_rcp_f32_e32 v35, v33
	s_nop 0
	v_mul_f32_e32 v34, 1.0, v35
	v_mov_b32_e32 v33, v34
	v_add_f32_e32 v34, 1.0, v203
	v_cvt_f16_f32_e32 v125, v213
	v_cvt_f16_f32_e32 v124, v212
	v_mov_b32_e32 v206, v123
	v_rcp_f32_e32 v36, v34
	s_nop 0
	v_mul_f32_e32 v35, 1.0, v36
	v_mov_b32_e32 v34, v35
	v_add_f32_e32 v35, 1.0, v202
	v_cvt_f16_f32_e32 v123, v211
	v_cvt_f16_f32_e32 v122, v210
	v_cvt_f16_f32_e32 v121, v209
	v_rcp_f32_e32 v37, v35
	s_nop 0
	v_mul_f32_e32 v36, 1.0, v37
	v_mov_b32_e32 v35, v36
	v_add_f32_e32 v36, 1.0, v201
	v_cvt_f16_f32_e32 v120, v208
	v_cvt_f16_f32_e32 v119, v207
	v_cvt_f16_f32_e32 v118, v206
	v_rcp_f32_e32 v38, v36
	s_nop 0
	v_mul_f32_e32 v37, 1.0, v38
	v_mov_b32_e32 v36, v37
	v_add_f32_e32 v37, 1.0, v200
	v_cvt_f16_f32_e32 v36, v36
	v_rcp_f32_e32 v39, v37
	s_nop 0
	v_mul_f32_e32 v38, 1.0, v39
	v_mov_b32_e32 v37, v38
	v_add_f32_e32 v38, 1.0, v199
	v_cvt_f16_f32_e32 v37, v37
	v_rcp_f32_e32 v40, v38
	s_nop 0
	v_mul_f32_e32 v39, 1.0, v40
	v_mov_b32_e32 v38, v39
	v_add_f32_e32 v39, 1.0, v198
	v_cvt_f16_f32_e32 v38, v38
	v_rcp_f32_e32 v41, v39
	s_nop 0
	v_mul_f32_e32 v40, 1.0, v41
	v_mov_b32_e32 v39, v40
	v_add_f32_e32 v40, 1.0, v197
	v_cvt_f16_f32_e32 v39, v39
	v_rcp_f32_e32 v42, v40
	s_nop 0
	v_mul_f32_e32 v41, 1.0, v42
	v_mov_b32_e32 v40, v41
	v_add_f32_e32 v41, 1.0, v196
	v_cvt_f16_f32_e32 v40, v40
	v_rcp_f32_e32 v43, v41
	s_nop 0
	v_mul_f32_e32 v42, 1.0, v43
	v_mov_b32_e32 v41, v42
	v_add_f32_e32 v42, 1.0, v195
	v_cvt_f16_f32_e32 v41, v41
	v_rcp_f32_e32 v44, v42
	s_nop 0
	v_mul_f32_e32 v43, 1.0, v44
	v_mov_b32_e32 v42, v43
	v_add_f32_e32 v43, 1.0, v194
	v_cvt_f16_f32_e32 v42, v42
	v_rcp_f32_e32 v45, v43
	s_nop 0
	v_mul_f32_e32 v44, 1.0, v45
	v_mov_b32_e32 v43, v44
	v_add_f32_e32 v44, 1.0, v193
	v_cvt_f16_f32_e32 v43, v43
	v_rcp_f32_e32 v46, v44
	s_nop 0
	v_mul_f32_e32 v45, 1.0, v46
	v_mov_b32_e32 v44, v45
	v_add_f32_e32 v45, 1.0, v192
	v_cvt_f16_f32_e32 v44, v44
	v_rcp_f32_e32 v47, v45
	s_nop 0
	v_mul_f32_e32 v46, 1.0, v47
	v_mov_b32_e32 v45, v46
	v_add_f32_e32 v46, 1.0, v170
	v_cvt_f16_f32_e32 v45, v45
	v_rcp_f32_e32 v48, v46
	s_nop 0
	v_mul_f32_e32 v47, 1.0, v48
	v_mov_b32_e32 v46, v47
	v_add_f32_e32 v47, 1.0, v169
	v_cvt_f16_f32_e32 v46, v46
	v_rcp_f32_e32 v49, v47
	s_nop 0
	v_mul_f32_e32 v48, 1.0, v49
	v_mov_b32_e32 v47, v48
	v_cvt_f16_f32_e32 v48, v32
	v_cvt_f16_f32_e32 v49, v33
	v_cvt_f16_f32_e32 v50, v34
	v_cvt_f16_f32_e32 v51, v35
	v_cvt_f32_f16_sdwa v33, v106 dst_sel:DWORD dst_unused:UNUSED_PAD src0_sel:WORD_1
	v_cvt_f32_f16_e32 v32, v106
	v_cvt_f32_f16_e32 v35, v48
	v_cvt_f32_f16_e32 v34, v133
	v_cvt_f16_f32_e32 v47, v47
	v_pk_fma_f32 v[28:29], v[28:29], v[34:35], v[32:33]
	s_nop 0
	v_cvt_pk_f16_f32 v106, v28, v29
	v_cvt_f32_f16_sdwa v29, v107 dst_sel:DWORD dst_unused:UNUSED_PAD src0_sel:WORD_1
	v_cvt_f32_f16_e32 v28, v107
	v_cvt_f32_f16_e32 v33, v49
	v_cvt_f32_f16_e32 v32, v132
	v_pk_fma_f32 v[28:29], v[30:31], v[32:33], v[28:29]
	s_nop 0
	v_cvt_pk_f16_f32 v107, v28, v29
	v_cvt_f32_f16_sdwa v29, v104 dst_sel:DWORD dst_unused:UNUSED_PAD src0_sel:WORD_1
	v_cvt_f32_f16_e32 v28, v104
	v_cvt_f32_f16_e32 v31, v50
	v_cvt_f32_f16_e32 v30, v131
	v_pk_fma_f32 v[24:25], v[24:25], v[30:31], v[28:29]
	s_nop 0
	v_cvt_pk_f16_f32 v104, v24, v25
	v_cvt_f32_f16_sdwa v25, v105 dst_sel:DWORD dst_unused:UNUSED_PAD src0_sel:WORD_1
	v_cvt_f32_f16_e32 v24, v105
	v_cvt_f32_f16_e32 v29, v51
	v_cvt_f32_f16_e32 v28, v130
	v_pk_fma_f32 v[24:25], v[26:27], v[28:29], v[24:25]
	s_nop 0
	v_cvt_pk_f16_f32 v105, v24, v25
	v_cvt_f32_f16_sdwa v25, v98 dst_sel:DWORD dst_unused:UNUSED_PAD src0_sel:WORD_1
	v_cvt_f32_f16_e32 v24, v98
	v_cvt_f32_f16_e32 v27, v36
	v_cvt_f32_f16_e32 v26, v129
	v_pk_fma_f32 v[20:21], v[20:21], v[26:27], v[24:25]
	s_nop 0
	v_cvt_pk_f16_f32 v98, v20, v21
	v_cvt_f32_f16_sdwa v21, v99 dst_sel:DWORD dst_unused:UNUSED_PAD src0_sel:WORD_1
	v_cvt_f32_f16_e32 v20, v99
	v_cvt_f32_f16_e32 v25, v37
	v_cvt_f32_f16_e32 v24, v128
	v_pk_fma_f32 v[20:21], v[22:23], v[24:25], v[20:21]
	s_nop 0
	v_cvt_pk_f16_f32 v99, v20, v21
	v_cvt_f32_f16_sdwa v21, v96 dst_sel:DWORD dst_unused:UNUSED_PAD src0_sel:WORD_1
	v_cvt_f32_f16_e32 v20, v96
	v_cvt_f32_f16_e32 v23, v38
	v_cvt_f32_f16_e32 v22, v127
	v_pk_fma_f32 v[16:17], v[16:17], v[22:23], v[20:21]
	s_nop 0
	v_cvt_pk_f16_f32 v96, v16, v17
	v_cvt_f32_f16_sdwa v17, v97 dst_sel:DWORD dst_unused:UNUSED_PAD src0_sel:WORD_1
	v_cvt_f32_f16_e32 v16, v97
	v_cvt_f32_f16_e32 v21, v39
	v_cvt_f32_f16_e32 v20, v126
	v_pk_fma_f32 v[16:17], v[18:19], v[20:21], v[16:17]
	s_nop 0
	v_cvt_pk_f16_f32 v97, v16, v17
	v_cvt_f32_f16_sdwa v17, v90 dst_sel:DWORD dst_unused:UNUSED_PAD src0_sel:WORD_1
	v_cvt_f32_f16_e32 v16, v90
	v_cvt_f32_f16_e32 v19, v40
	v_cvt_f32_f16_e32 v18, v125
	v_pk_fma_f32 v[12:13], v[12:13], v[18:19], v[16:17]
	s_nop 0
	v_cvt_pk_f16_f32 v90, v12, v13
	v_cvt_f32_f16_sdwa v13, v91 dst_sel:DWORD dst_unused:UNUSED_PAD src0_sel:WORD_1
	v_cvt_f32_f16_e32 v12, v91
	v_cvt_f32_f16_e32 v17, v41
	v_cvt_f32_f16_e32 v16, v124
	v_pk_fma_f32 v[12:13], v[14:15], v[16:17], v[12:13]
	s_nop 0
	v_cvt_pk_f16_f32 v91, v12, v13
	v_cvt_f32_f16_sdwa v13, v88 dst_sel:DWORD dst_unused:UNUSED_PAD src0_sel:WORD_1
	v_cvt_f32_f16_e32 v12, v88
	v_cvt_f32_f16_e32 v15, v42
	v_cvt_f32_f16_e32 v14, v123
	v_pk_fma_f32 v[8:9], v[8:9], v[14:15], v[12:13]
	s_nop 0
	v_cvt_pk_f16_f32 v88, v8, v9
	v_cvt_f32_f16_sdwa v9, v89 dst_sel:DWORD dst_unused:UNUSED_PAD src0_sel:WORD_1
	v_cvt_f32_f16_e32 v8, v89
	v_cvt_f32_f16_e32 v13, v43
	v_cvt_f32_f16_e32 v12, v122
	v_pk_fma_f32 v[8:9], v[10:11], v[12:13], v[8:9]
	s_nop 0
	v_cvt_pk_f16_f32 v89, v8, v9
	v_cvt_f32_f16_sdwa v9, v82 dst_sel:DWORD dst_unused:UNUSED_PAD src0_sel:WORD_1
	v_cvt_f32_f16_e32 v8, v82
	v_cvt_f32_f16_e32 v11, v44
	v_cvt_f32_f16_e32 v10, v121
	v_pk_fma_f32 v[4:5], v[4:5], v[10:11], v[8:9]
	s_nop 0
	v_cvt_pk_f16_f32 v82, v4, v5
	v_cvt_f32_f16_sdwa v5, v83 dst_sel:DWORD dst_unused:UNUSED_PAD src0_sel:WORD_1
	v_cvt_f32_f16_e32 v4, v83
	v_cvt_f32_f16_e32 v9, v45
	v_cvt_f32_f16_e32 v8, v120
	v_pk_fma_f32 v[4:5], v[6:7], v[8:9], v[4:5]
	s_nop 0
	v_cvt_pk_f16_f32 v83, v4, v5
	v_cvt_f32_f16_sdwa v5, v80 dst_sel:DWORD dst_unused:UNUSED_PAD src0_sel:WORD_1
	v_cvt_f32_f16_e32 v4, v80
	v_cvt_f32_f16_e32 v7, v46
	v_cvt_f32_f16_e32 v6, v119
	v_pk_fma_f32 v[0:1], v[0:1], v[6:7], v[4:5]
	s_nop 0
	v_cvt_pk_f16_f32 v80, v0, v1
	v_cvt_f32_f16_sdwa v1, v81 dst_sel:DWORD dst_unused:UNUSED_PAD src0_sel:WORD_1
	v_cvt_f32_f16_e32 v0, v81
	v_cvt_f32_f16_e32 v5, v47
	v_cvt_f32_f16_e32 v4, v118
	v_pk_fma_f32 v[0:1], v[2:3], v[4:5], v[0:1]
	s_nop 0
	v_cvt_pk_f16_f32 v81, v0, v1
	s_cbranch_scc1 .LBB0_1112
; template <int NJ, bool SPLIT = false>
; __device__ __forceinline__ void gemm_tile_dma(const f16* __restrict__ A, int lda, const f16* __restrict__ Bt, int ldb,
;                                               int K, f32x4 (&acc)[4][NJ], f16* sA, const int tid) {
;   constexpr int DSTAGE = 16384;
;   const int lane = tid & 63;
;   const int wave = __builtin_amdgcn_readfirstlane(tid >> 6);
;   const int wm = wave >> 1, wn = wave & 1;
;   const int lr = lane >> 3, ls = lane & 7;
;   const int ra = wave * 32 + lr;
;   const int rb = wave * (NJ * 8) + lr;
;   const f16* asrc = A + (size_t)ra * lda + ((ls ^ (ra & 7)) * 8);
;   const f16* bsrc = Bt + ((ls ^ (rb & 7)) * 8);
;   f16* adst = sA + (wave * 32) * 64;
;   f16* bdst = sA + 8192 + (wave * (NJ * 8)) * 64;
;   const int lq = lane & 15, g = lane >> 4;
;   const int rdA = (wm * 64 + lq) * 64;
;   const int rdB = 8192 + (wn * (NJ * 16) + lq) * 64;
;   const int sw0 = ((0 + g) ^ (lq & 7)) * 8, sw1 = ((4 + g) ^ (lq & 7)) * 8;
;     ...
;   __syncthreads();
;   D_STAGE(0, 0)
;   asm volatile("s_waitcnt vmcnt(0)" ::: "memory");
;   __syncthreads();
;   int cur = 0;
; __device__ __forceinline__ void phase_g2(const Params& p, int l, f16* smem) {
;     ...
;     for (int x = 0; x < 3; ++x) {
;       f16x4 sg[4][4];
;       {
;         f32x4 ag[4][4];
;         zero_acc<4>(ag);
;         gemm_tile_dma<4>(HP + (size_t)m0 * DM, DM, WG + (size_t)(x * DM + n0) * DM, DM, DM, ag, sA, TIDX(p));
.LBB0_1115:
	s_ashr_i32 s15, s14, 31
	s_lshl_b64 s[16:17], s[14:15], 11
	s_lshl_b32 s15, s9, 10
	v_readfirstlane_b32 s20, v156
	s_add_i32 s18, s15, s8
	s_ashr_i32 s15, s20, 6
	s_lshl_b32 s21, s15, 5
	v_or_b32_e32 v0, s21, v157
	v_ashrrev_i32_e32 v1, 31, v0
	v_lshlrev_b64 v[2:3], 11, v[0:1]
	s_lshl_b32 s15, s15, 12
	v_lshl_add_u64 v[4:5], v[110:111], 0, v[2:3]
	s_mov_b32 m0, s15
	s_barrier
	global_load_lds_dwordx4 v[4:5], off
	v_lshl_add_u64 v[6:7], v[4:5], 0, s[66:67]
	s_or_b32 m0, s15, 0x400
	s_ashr_i32 s19, s18, 31
	global_load_lds_dwordx4 v[6:7], off
	v_lshl_add_u64 v[6:7], v[4:5], 0, s[92:93]
	s_or_b32 m0, s15, 0x800
	s_lshl_b64 s[18:19], s[18:19], 11
	global_load_lds_dwordx4 v[6:7], off
	v_lshl_add_u64 v[4:5], v[4:5], 0, s[78:79]
	s_or_b32 m0, s15, 0xc00
	s_lshr_b32 s24, s20, 1
	global_load_lds_dwordx4 v[4:5], off
	v_lshl_add_u64 v[4:5], v[72:73], 0, s[18:19]
	s_add_i32 m0, s15, 0x4000
	v_lshl_add_u64 v[6:7], v[4:5], 0, v[2:3]
	global_load_lds_dwordx4 v[6:7], off
	v_or_b32_e32 v6, 8, v0
	v_ashrrev_i32_e32 v7, 31, v6
	v_lshlrev_b64 v[6:7], 11, v[6:7]
	v_lshl_add_u64 v[6:7], v[4:5], 0, v[6:7]
	s_add_i32 m0, s15, 0x4400
	s_and_b32 s24, s24, 0x1ffffc0
	global_load_lds_dwordx4 v[6:7], off
	v_or_b32_e32 v6, 16, v0
	v_ashrrev_i32_e32 v7, 31, v6
	v_or_b32_e32 v0, 24, v0
	v_lshlrev_b64 v[6:7], 11, v[6:7]
	v_ashrrev_i32_e32 v1, 31, v0
	v_lshl_add_u64 v[6:7], v[4:5], 0, v[6:7]
	s_add_i32 m0, s15, 0x4800
	v_lshlrev_b64 v[0:1], 11, v[0:1]
	global_load_lds_dwordx4 v[6:7], off
	v_lshl_add_u64 v[0:1], v[4:5], 0, v[0:1]
	s_add_i32 m0, s15, 0x4c00
	v_lshl_add_u64 v[4:5], v[76:77], 0, s[16:17]
	global_load_lds_dwordx4 v[0:1], off
	v_or_b32_e32 v0, s21, v161
	v_ashrrev_i32_e32 v1, 31, v0
	v_lshlrev_b64 v[0:1], 11, v[0:1]
	v_lshl_add_u64 v[118:119], v[4:5], 0, v[0:1]
	v_or_b32_e32 v0, s21, v162
	v_ashrrev_i32_e32 v1, 31, v0
	v_lshlrev_b64 v[0:1], 11, v[0:1]
	v_lshl_add_u64 v[120:121], v[4:5], 0, v[0:1]
	v_or_b32_e32 v0, s21, v163
	s_waitcnt vmcnt(0)
	v_ashrrev_i32_e32 v1, 31, v0
	v_and_or_b32 v8, s20, 64, v158
	v_or_b32_e32 v9, s24, v158
	v_lshlrev_b64 v[0:1], 11, v[0:1]
	v_lshlrev_b32_e32 v128, 7, v9
	v_lshlrev_b32_e32 v129, 7, v8
	v_lshl_add_u64 v[122:123], v[4:5], 0, v[0:1]
	v_lshl_add_u64 v[124:125], v[4:5], 0, v[2:3]
	v_lshl_add_u64 v[126:127], v[116:117], 0, v[2:3]
	s_mov_b32 s18, 0
	s_mov_b32 s19, 0
	v_mov_b32_e32 v12, 0
	v_mov_b32_e32 v13, v168
	v_mov_b32_e32 v14, v168
	v_mov_b32_e32 v15, v168
	v_mov_b32_e32 v24, 0
	v_mov_b32_e32 v25, v168
	v_mov_b32_e32 v26, v168
	v_mov_b32_e32 v27, v168
	v_mov_b32_e32 v32, 0
	v_mov_b32_e32 v33, v168
	v_mov_b32_e32 v34, v168
	v_mov_b32_e32 v35, v168
	v_mov_b32_e32 v0, 0
	v_mov_b32_e32 v1, v168
	v_mov_b32_e32 v2, v168
	v_mov_b32_e32 v3, v168
	v_mov_b32_e32 v4, 0
	v_mov_b32_e32 v5, v168
	v_mov_b32_e32 v6, v168
	v_mov_b32_e32 v7, v168
	v_mov_b32_e32 v8, 0
	v_mov_b32_e32 v9, v168
	v_mov_b32_e32 v10, v168
	v_mov_b32_e32 v11, v168
	v_mov_b32_e32 v16, 0
	v_mov_b32_e32 v17, v168
	v_mov_b32_e32 v18, v168
	v_mov_b32_e32 v19, v168
	v_mov_b32_e32 v20, 0
	v_mov_b32_e32 v21, v168
	v_mov_b32_e32 v22, v168
	v_mov_b32_e32 v23, v168
	v_mov_b32_e32 v28, 0
	v_mov_b32_e32 v29, v168
	v_mov_b32_e32 v30, v168
	v_mov_b32_e32 v31, v168
	v_mov_b32_e32 v36, 0
	v_mov_b32_e32 v37, v168
	v_mov_b32_e32 v38, v168
	v_mov_b32_e32 v39, v168
	v_mov_b32_e32 v40, 0
	v_mov_b32_e32 v41, v168
	v_mov_b32_e32 v42, v168
	v_mov_b32_e32 v43, v168
	v_mov_b32_e32 v44, 0
	v_mov_b32_e32 v45, v168
	v_mov_b32_e32 v46, v168
	v_mov_b32_e32 v47, v168
	v_mov_b32_e32 v48, 0
	v_mov_b32_e32 v49, v168
	v_mov_b32_e32 v50, v168
	v_mov_b32_e32 v51, v168
	v_mov_b32_e32 v52, 0
	v_mov_b32_e32 v53, v168
	v_mov_b32_e32 v54, v168
	v_mov_b32_e32 v55, v168
	v_mov_b32_e32 v56, 0
	v_mov_b32_e32 v57, v168
	v_mov_b32_e32 v58, v168
	v_mov_b32_e32 v59, v168
	v_mov_b32_e32 v60, 0
	v_mov_b32_e32 v61, v168
	v_mov_b32_e32 v62, v168
	v_mov_b32_e32 v63, v168
	s_waitcnt vmcnt(0) lgkmcnt(0)
	s_barrier
	s_bitcmp1_b32 s95, 8
	s_cbranch_scc0 .Lprio_g2_1117
	s_setprio 1
.Lprio_g2_1117:
	s_branch .LBB0_1117

; __device__ __forceinline__ float sigmoidf_(float x) { return 1.0f / (1.0f + __expf(-x)); }
; template <int NJ, bool SPLIT = false>
; __device__ __forceinline__ void gemm_tile_dma(const f16* __restrict__ A, int lda, const f16* __restrict__ Bt, int ldb,
;                                               int K, f32x4 (&acc)[4][NJ], f16* sA, const int tid) {
;     ...
;   __syncthreads();
; __device__ __forceinline__ void phase_g2(const Params& p, int l, f16* smem) {
;     ...
; #pragma unroll
;         for (int i = 0; i < 4; ++i)
; #pragma unroll
;           for (int j = 0; j < 4; ++j)
; #pragma unroll
;             for (int r = 0; r < 4; ++r) sg[i][j][r] = (f16)sigmoidf_(ag[i][j][r]);
;       }
;       __builtin_amdgcn_sched_barrier(0);
;       const f16* wo = (const f16*)(p.ws + (x == 0 ? WT_RO_OFF : (x == 1 ? WT_PO_OFF : WT_NO_OFF)));
;       const int kx = x == 1 ? 256 : RD;
;       const int aoff = x == 0 ? 0 : (x == 1 ? RD : 640);
; #pragma unroll
;       for (int h = 0; h < 2; ++h) {
;         f32x4 ab[4][2];
;         zero_acc<2>(ab);
;         gemm_tile_dma<2, true>(BR + (size_t)m0 * DM + aoff, DM, wo + (size_t)(n0 + h * 32) * kx, kx, kx, ab, sA, TIDX(p));
.LBB0_1119:
	s_setprio 0
	s_nop 3
	v_mul_f32_e32 v0, 0xbfb8aa3b, v0
	v_exp_f32_e32 v124, v0
	v_mul_f32_e32 v0, 0xbfb8aa3b, v1
	v_exp_f32_e32 v125, v0
	v_mul_f32_e32 v0, 0xbfb8aa3b, v2
	v_exp_f32_e32 v122, v0
	v_mul_f32_e32 v0, 0xbfb8aa3b, v3
	v_exp_f32_e32 v123, v0
	v_mul_f32_e32 v0, 0xbfb8aa3b, v32
	v_exp_f32_e32 v120, v0
	v_mul_f32_e32 v0, 0xbfb8aa3b, v33
	v_exp_f32_e32 v121, v0
	v_mul_f32_e32 v0, 0xbfb8aa3b, v34
	v_exp_f32_e32 v118, v0
	v_mul_f32_e32 v0, 0xbfb8aa3b, v35
	v_exp_f32_e32 v119, v0
	v_mul_f32_e32 v0, 0xbfb8aa3b, v24
	v_exp_f32_e32 v209, v0
	v_mul_f32_e32 v0, 0xbfb8aa3b, v25
	v_exp_f32_e32 v193, v0
	v_mul_f32_e32 v0, 0xbfb8aa3b, v26
	v_exp_f32_e32 v208, v0
	v_mul_f32_e32 v0, 0xbfb8aa3b, v27
	v_mul_f32_e32 v60, 0xbfb8aa3b, v60
	v_mul_f32_e32 v56, 0xbfb8aa3b, v56
	v_mul_f32_e32 v52, 0xbfb8aa3b, v52
	v_mul_f32_e32 v48, 0xbfb8aa3b, v48
	v_mul_f32_e32 v44, 0xbfb8aa3b, v44
	v_mul_f32_e32 v40, 0xbfb8aa3b, v40
	v_mul_f32_e32 v36, 0xbfb8aa3b, v36
	v_mul_f32_e32 v28, 0xbfb8aa3b, v28
	v_mul_f32_e32 v20, 0xbfb8aa3b, v20
	v_mul_f32_e32 v16, 0xbfb8aa3b, v16
	v_mul_f32_e32 v8, 0xbfb8aa3b, v8
	v_mul_f32_e32 v4, 0xbfb8aa3b, v4
	v_exp_f32_e32 v192, v0
	v_mul_f32_e32 v0, 0xbfb8aa3b, v12
	v_exp_f32_e32 v148, v60
	v_mul_f32_e32 v60, 0xbfb8aa3b, v61
	v_exp_f32_e32 v144, v56
	v_mul_f32_e32 v56, 0xbfb8aa3b, v57
	v_exp_f32_e32 v221, v52
	v_mul_f32_e32 v52, 0xbfb8aa3b, v53
	v_exp_f32_e32 v219, v48
	v_mul_f32_e32 v48, 0xbfb8aa3b, v49
	v_exp_f32_e32 v140, v44
	v_mul_f32_e32 v44, 0xbfb8aa3b, v45
	v_exp_f32_e32 v136, v40
	v_mul_f32_e32 v40, 0xbfb8aa3b, v41
	v_exp_f32_e32 v217, v36
	v_mul_f32_e32 v36, 0xbfb8aa3b, v37
	v_exp_f32_e32 v215, v28
	v_mul_f32_e32 v28, 0xbfb8aa3b, v29
	v_exp_f32_e32 v132, v20
	v_mul_f32_e32 v20, 0xbfb8aa3b, v21
	v_exp_f32_e32 v128, v16
	v_mul_f32_e32 v16, 0xbfb8aa3b, v17
	v_exp_f32_e32 v213, v8
	v_mul_f32_e32 v8, 0xbfb8aa3b, v9
	v_exp_f32_e32 v211, v4
	v_mul_f32_e32 v4, 0xbfb8aa3b, v5
	v_exp_f32_e32 v207, v0
	v_mul_f32_e32 v0, 0xbfb8aa3b, v13
	v_exp_f32_e32 v149, v60
	v_mul_f32_e32 v60, 0xbfb8aa3b, v62
	v_exp_f32_e32 v145, v56
	v_mul_f32_e32 v56, 0xbfb8aa3b, v58
	v_exp_f32_e32 v205, v52
	v_mul_f32_e32 v52, 0xbfb8aa3b, v54
	v_exp_f32_e32 v203, v48
	v_mul_f32_e32 v48, 0xbfb8aa3b, v50
	v_exp_f32_e32 v141, v44
	v_mul_f32_e32 v44, 0xbfb8aa3b, v46
	v_exp_f32_e32 v137, v40
	v_mul_f32_e32 v40, 0xbfb8aa3b, v42
	v_exp_f32_e32 v201, v36
	v_mul_f32_e32 v36, 0xbfb8aa3b, v38
	v_exp_f32_e32 v199, v28
	v_mul_f32_e32 v28, 0xbfb8aa3b, v30
	v_exp_f32_e32 v133, v20
	v_mul_f32_e32 v20, 0xbfb8aa3b, v22
	v_exp_f32_e32 v129, v16
	v_mul_f32_e32 v16, 0xbfb8aa3b, v18
	v_exp_f32_e32 v197, v8
	v_mul_f32_e32 v8, 0xbfb8aa3b, v10
	v_exp_f32_e32 v195, v4
	v_mul_f32_e32 v4, 0xbfb8aa3b, v6
	v_exp_f32_e32 v170, v0
	v_mul_f32_e32 v0, 0xbfb8aa3b, v14
	v_exp_f32_e32 v146, v60
	v_mul_f32_e32 v60, 0xbfb8aa3b, v63
	v_exp_f32_e32 v142, v56
	v_mul_f32_e32 v56, 0xbfb8aa3b, v59
	v_exp_f32_e32 v220, v52
	v_mul_f32_e32 v52, 0xbfb8aa3b, v55
	v_exp_f32_e32 v218, v48
	v_mul_f32_e32 v48, 0xbfb8aa3b, v51
	v_exp_f32_e32 v138, v44
	v_mul_f32_e32 v44, 0xbfb8aa3b, v47
	v_exp_f32_e32 v134, v40
	v_mul_f32_e32 v40, 0xbfb8aa3b, v43
	v_exp_f32_e32 v216, v36
	v_mul_f32_e32 v36, 0xbfb8aa3b, v39
	v_exp_f32_e32 v214, v28
	v_mul_f32_e32 v28, 0xbfb8aa3b, v31
	v_exp_f32_e32 v130, v20
	v_mul_f32_e32 v20, 0xbfb8aa3b, v23
	v_exp_f32_e32 v126, v16
	v_mul_f32_e32 v16, 0xbfb8aa3b, v19
	v_exp_f32_e32 v212, v8
	v_mul_f32_e32 v8, 0xbfb8aa3b, v11
	v_exp_f32_e32 v210, v4
	v_mul_f32_e32 v4, 0xbfb8aa3b, v7
	v_exp_f32_e32 v206, v0
	v_mul_f32_e32 v0, 0xbfb8aa3b, v15
	v_exp_f32_e32 v147, v60
	v_exp_f32_e32 v143, v56
	v_exp_f32_e32 v204, v52
	v_exp_f32_e32 v202, v48
	v_exp_f32_e32 v139, v44
	v_exp_f32_e32 v135, v40
	v_exp_f32_e32 v200, v36
	v_exp_f32_e32 v198, v28
	v_exp_f32_e32 v131, v20
	v_exp_f32_e32 v127, v16
	v_exp_f32_e32 v196, v8
	v_exp_f32_e32 v194, v4
	v_exp_f32_e32 v169, v0
	s_cmp_eq_u32 s9, 1
	s_mov_b32 s15, 0xc90000
	s_movk_i32 s17, 0x280
	s_cselect_b32 s16, s15, 0xd10000
	s_cselect_b32 s15, 0x100, s60
	s_cselect_b32 s18, 0x180, s17
	s_cmp_eq_u32 s9, 0
	v_readfirstlane_b32 s21, v156
	s_cselect_b32 s16, 0xbd0000, s16
	s_cselect_b32 s18, 0, s18
	s_ashr_i32 s24, s21, 6
	s_lshl_b32 s25, s24, 5
	v_or_b32_e32 v4, s25, v157
	s_lshl_b32 s42, s18, 1
	v_ashrrev_i32_e32 v5, 31, v4
	v_lshl_add_u64 v[2:3], v[114:115], 0, s[42:43]
	v_lshlrev_b64 v[12:13], 11, v[4:5]
	s_lshl_b32 s20, s24, 12
	v_lshl_add_u64 v[4:5], v[2:3], 0, v[12:13]
	s_mov_b32 m0, s20
	s_barrier
; template <int NJ, bool SPLIT = false>
; __device__ __forceinline__ void gemm_tile_dma(const f16* __restrict__ A, int lda, const f16* __restrict__ Bt, int ldb,
;                                               int K, f32x4 (&acc)[4][NJ], f16* sA, const int tid) {
;     ...
;   __syncthreads();
;   D_STAGE(0, 0)
;   asm volatile("s_waitcnt vmcnt(0)" ::: "memory");
;   __syncthreads();
; __device__ __forceinline__ void phase_g2(const Params& p, int l, f16* smem) {
;     ...
;         f32x4 ab[4][2];
;         zero_acc<2>(ab);
;         gemm_tile_dma<2, true>(BR + (size_t)m0 * DM + aoff, DM, wo + (size_t)(n0 + h * 32) * kx, kx, kx, ab, sA, TIDX(p));
	global_load_lds_dwordx4 v[4:5], off
	v_lshl_add_u64 v[6:7], v[4:5], 0, s[66:67]
	s_or_b32 m0, s20, 0x400
	s_mov_b32 s17, 0
	global_load_lds_dwordx4 v[6:7], off
	v_lshl_add_u64 v[6:7], v[4:5], 0, s[92:93]
	s_or_b32 m0, s20, 0x800
	v_lshl_add_u64 v[0:1], v[68:69], 0, s[16:17]
	s_mul_hi_i32 s19, s15, s8
	s_mul_i32 s18, s15, s8
	s_lshl_b32 s36, s24, 4
	global_load_lds_dwordx4 v[6:7], off
	v_lshl_add_u64 v[4:5], v[4:5], 0, s[78:79]
	s_or_b32 m0, s20, 0xc00
	s_ashr_i32 s21, s21, 1
	global_load_lds_dwordx4 v[4:5], off
	v_lshl_add_u64 v[4:5], s[18:19], 1, v[0:1]
	s_lshl_b32 s18, s24, 11
	s_and_b32 s24, s36, 16
	s_and_b32 s37, s21, 0xffffffc0
	v_or_b32_e32 v6, s24, v157
	v_or_b32_e32 v8, s37, v6
	s_sub_i32 s21, s20, s18
	v_mad_i64_i32 v[6:7], s[18:19], v8, s15, 0
	s_add_i32 m0, s21, 0x4000
	v_lshl_add_u64 v[6:7], v[6:7], 1, v[4:5]
	global_load_lds_dwordx4 v[6:7], off
	v_or_b32_e32 v6, 8, v8
	v_mad_i64_i32 v[6:7], s[18:19], v6, s15, 0
	v_lshl_add_u64 v[4:5], v[6:7], 1, v[4:5]
	s_add_i32 m0, s21, 0x4400
	v_mov_b32_e32 v32, 0
	global_load_lds_dwordx4 v[4:5], off
	v_and_or_b32 v4, s25, 32, v158
	v_lshlrev_b32_e32 v15, 7, v4
	v_or_b32_e32 v4, s37, v163
	v_or_b32_e32 v5, s37, v158
	v_or_b32_e32 v4, s24, v4
	v_lshlrev_b32_e32 v14, 7, v5
	v_ashrrev_i32_e32 v5, 31, v4
	v_lshl_add_u64 v[6:7], v[4:5], 1, s[10:11]
	v_lshl_add_u64 v[4:5], v[78:79], 0, s[16:17]
	v_mad_u64_u32 v[8:9], s[18:19], v6, s15, v[4:5]
	v_or_b32_e32 v6, s37, v157
	v_or_b32_e32 v6, s24, v6
	v_mad_i32_i24 v9, v7, s15, v9
	v_ashrrev_i32_e32 v7, 31, v6
	v_lshl_add_u64 v[6:7], v[6:7], 1, s[10:11]
	s_waitcnt vmcnt(0)
	v_mad_u64_u32 v[10:11], s[18:19], v6, s15, v[4:5]
	v_mad_i32_i24 v11, v7, s15, v11
	v_lshl_add_u64 v[6:7], v[116:117], 0, s[42:43]
	v_lshl_add_u64 v[12:13], v[6:7], 0, v[12:13]
	s_mov_b32 s16, 64
	v_mov_b32_e32 v33, v32
	v_mov_b32_e32 v34, v32
	v_mov_b32_e32 v35, v32
	v_mov_b32_e32 v36, v32
	v_mov_b32_e32 v37, v32
	v_mov_b32_e32 v38, v32
	v_mov_b32_e32 v39, v32
	v_mov_b32_e32 v40, v32
	v_mov_b32_e32 v41, v32
	v_mov_b32_e32 v42, v32
	v_mov_b32_e32 v43, v32
	v_mov_b32_e32 v44, v32
	v_mov_b32_e32 v45, v32
	v_mov_b32_e32 v46, v32
	v_mov_b32_e32 v47, v32
	v_mov_b32_e32 v48, v32
	v_mov_b32_e32 v49, v32
	v_mov_b32_e32 v50, v32
	v_mov_b32_e32 v51, v32
	v_mov_b32_e32 v52, v32
	v_mov_b32_e32 v53, v32
	v_mov_b32_e32 v54, v32
	v_mov_b32_e32 v55, v32
	v_mov_b32_e32 v56, v32
	v_mov_b32_e32 v57, v32
	v_mov_b32_e32 v58, v32
	v_mov_b32_e32 v59, v32
	v_mov_b32_e32 v60, v32
	v_mov_b32_e32 v61, v32
	v_mov_b32_e32 v62, v32
	v_mov_b32_e32 v63, v32
	s_waitcnt vmcnt(0) lgkmcnt(0)
	s_barrier
	s_bitcmp1_b32 s95, 8
	s_cbranch_scc0 .Lprio_g2_1121
	s_setprio 1

; template <int NJ, bool SPLIT = false>
; __device__ __forceinline__ void gemm_tile_dma(const f16* __restrict__ A, int lda, const f16* __restrict__ Bt, int ldb,
;                                               int K, f32x4 (&acc)[4][NJ], f16* sA, const int tid) {
;     ...
;   __syncthreads();
;   D_STAGE(0, 0)
;   asm volatile("s_waitcnt vmcnt(0)" ::: "memory");
;   __syncthreads();
; __device__ __forceinline__ void phase_g2(const Params& p, int l, f16* smem) {
;     ...
;       for (int h = 0; h < 2; ++h) {
;         f32x4 ab[4][2];
;         zero_acc<2>(ab);
;         gemm_tile_dma<2, true>(BR + (size_t)m0 * DM + aoff, DM, wo + (size_t)(n0 + h * 32) * kx, kx, kx, ab, sA, TIDX(p));
.LBB0_1123:
	s_setprio 0
	v_readfirstlane_b32 s19, v156
	s_ashr_i32 s20, s19, 6
	s_lshl_b32 s21, s20, 5
	v_or_b32_e32 v8, s21, v157
	v_ashrrev_i32_e32 v9, 31, v8
	v_lshlrev_b64 v[8:9], 11, v[8:9]
	s_lshl_b32 s18, s20, 12
	v_lshl_add_u64 v[2:3], v[2:3], 0, v[8:9]
	s_mov_b32 m0, s18
	s_barrier
	global_load_lds_dwordx4 v[2:3], off
	v_lshl_add_u64 v[10:11], v[2:3], 0, s[66:67]
	s_or_b32 m0, s18, 0x400
	s_mul_hi_i32 s17, s15, s7
	s_mul_i32 s16, s15, s7
	s_lshl_b32 s24, s20, 4
	global_load_lds_dwordx4 v[10:11], off
	v_lshl_add_u64 v[10:11], v[2:3], 0, s[92:93]
	s_or_b32 m0, s18, 0x800
	s_ashr_i32 s19, s19, 1
	global_load_lds_dwordx4 v[10:11], off
	v_lshl_add_u64 v[2:3], v[2:3], 0, s[78:79]
	s_or_b32 m0, s18, 0xc00
	v_lshl_add_u64 v[0:1], s[16:17], 1, v[0:1]
	s_lshl_b32 s16, s20, 11
	s_and_b32 s20, s24, 16
	s_and_b32 s25, s19, 0xffffffc0
	global_load_lds_dwordx4 v[2:3], off
	v_or_b32_e32 v2, s20, v157
	v_or_b32_e32 v10, s25, v2
	s_sub_i32 s19, s18, s16
	v_mad_i64_i32 v[2:3], s[16:17], v10, s15, 0
	s_add_i32 m0, s19, 0x4000
	v_lshl_add_u64 v[2:3], v[2:3], 1, v[0:1]
	global_load_lds_dwordx4 v[2:3], off
	v_or_b32_e32 v2, 8, v10
	v_mad_i64_i32 v[2:3], s[16:17], v2, s15, 0
	v_lshl_add_u64 v[0:1], v[2:3], 1, v[0:1]
	s_add_i32 m0, s19, 0x4400
	v_lshl_add_u64 v[154:155], v[6:7], 0, v[8:9]
	global_load_lds_dwordx4 v[0:1], off
	v_and_or_b32 v0, s21, 32, v158
	v_lshlrev_b32_e32 v223, 7, v0
	v_or_b32_e32 v0, s25, v163
	v_or_b32_e32 v1, s25, v158
	v_or_b32_e32 v0, s20, v0
	v_lshlrev_b32_e32 v222, 7, v1
	v_ashrrev_i32_e32 v1, 31, v0
	v_lshl_add_u64 v[0:1], v[0:1], 1, s[12:13]
	v_mad_u64_u32 v[150:151], s[16:17], v0, s15, v[4:5]
	v_mov_b32_e32 v0, v151
	v_mad_u64_u32 v[0:1], s[16:17], v1, s15, v[0:1]
	v_mov_b32_e32 v151, v0
	v_or_b32_e32 v0, s25, v157
	v_or_b32_e32 v0, s20, v0
	v_ashrrev_i32_e32 v1, 31, v0
	v_lshl_add_u64 v[0:1], v[0:1], 1, s[12:13]
	v_mad_u64_u32 v[152:153], s[16:17], v0, s15, v[4:5]
	v_mov_b32_e32 v0, v153
	s_waitcnt vmcnt(0)
	v_mad_u64_u32 v[0:1], s[16:17], v1, s15, v[0:1]
	v_mov_b32_e32 v153, v0
	v_mov_b32_e32 v0, 0
	s_mov_b32 s20, 0
	s_mov_b32 s21, 64
	v_mov_b32_e32 v1, v0
	v_mov_b32_e32 v2, v0
	v_mov_b32_e32 v3, v0
	v_mov_b32_e32 v4, v0
	v_mov_b32_e32 v5, v0
	v_mov_b32_e32 v6, v0
	v_mov_b32_e32 v7, v0
	v_mov_b32_e32 v8, v0
	v_mov_b32_e32 v9, v0
	v_mov_b32_e32 v10, v0
	v_mov_b32_e32 v11, v0
	v_mov_b32_e32 v12, v0
	v_mov_b32_e32 v13, v0
	v_mov_b32_e32 v14, v0
	v_mov_b32_e32 v15, v0
	v_mov_b32_e32 v16, v0
	v_mov_b32_e32 v17, v0
	v_mov_b32_e32 v18, v0
	v_mov_b32_e32 v19, v0
	v_mov_b32_e32 v20, v0
	v_mov_b32_e32 v21, v0
	v_mov_b32_e32 v22, v0
	v_mov_b32_e32 v23, v0
	v_mov_b32_e32 v24, v0
	v_mov_b32_e32 v25, v0
	v_mov_b32_e32 v26, v0
	v_mov_b32_e32 v27, v0
	v_mov_b32_e32 v28, v0
	v_mov_b32_e32 v29, v0
	v_mov_b32_e32 v30, v0
	v_mov_b32_e32 v31, v0
	s_waitcnt vmcnt(0) lgkmcnt(0)
	s_barrier
	s_bitcmp1_b32 s95, 8
	s_cbranch_scc0 .Lprio_g2_1125
	s_setprio 1
